# adds: diff-attn re-max decision moved after the exps (row half-sums >128 trigger exact power-of-two rescale of the f32 exps, o, l and m); row-max tree removed from the common path, exps spread under 7
# speedup vs baseline: 1.0733x; 1.0199x over previous
; DI int tid_() { int t = threadIdx.x; asm volatile("" : "+v"(t)); return t; }
; DI void diff_unit(KP p, int l, int b, int h, int qb, int isctx, float lamv, float lam_init, char* ldsc) {
;   const int tid = tid_(), lane = tid & 63, w = __builtin_amdgcn_readfirstlane(tid >> 6), r = lane & 31, hh = lane >> 5;
;   const int pr = (r & ~12) | ((r & 4) << 1) | ((r & 8) >> 1);
;   const int comp = w & 1, grp = w >> 1;
;   const int qrow = (isctx ? TL + b * CTXL : b * SEQ) + qb * 128 + grp * 32 + r;
;   const int nt = isctx ? 4 : 132;
;   lds_u8* L = (lds_u8*)ldsc;
;   constexpr int STG = 32768;
;   int ko[4], vo[4];
; #pragma unroll
;   for (int ks = 0; ks < 4; ++ks) ko[ks] = pr * 128 + (((2 * ks + hh) ^ ((pr >> 1) & 7)) << 4);
; #pragma unroll
;   for (int q = 0; q < 4; ++q) vo[q] = r * 128 + (((2 * q + hh) ^ ((r >> 1) & 7)) << 4);
;   bf16x8 qf[4];
; #pragma unroll
;   for (int ks = 0; ks < 4; ++ks) qf[ks] = *(const bf16x8*)(p->P + (size_t)qrow * INC + 512 + h * 128 + comp * 64 + 16 * ks + 8 * hh);
;   f32x16 o[4];
; #pragma unroll
;   for (int d = 0; d < 4; ++d)
; #pragma unroll
;     for (int i = 0; i < 16; ++i) o[d][i] = 0.f;
;   float m, lsum;
;   const bf16_t* vt = p->Vtd + (size_t)((b * 4 + h) * 128) * NKEY;
;   const bf16_t* Pk = p->P + 1024 + h * 128;
;   const int row8 = 8 * w + (lane >> 3), swz = ((lane & 7) ^ ((row8 >> 1) & 7)) << 4;
;   const unsigned kq = (unsigned)(row8 * (INC * 2) + swz), vq = (unsigned)(row8 * (NKEY * 2) + swz);
;     ...
;   asm volatile("s_waitcnt vmcnt(0)" ::: "memory");
;   __syncthreads();
;   DISSUE(0, 0);
;   DISSUE(1, 1);
;   asm volatile("s_waitcnt vmcnt(4)" ::: "memory");
;   __builtin_amdgcn_s_barrier();
;   bf16x8 P[4];
;   {
;     f32x16 st[2];
;     qk_tile(qf, L + comp * 8192, ko, st);
;     m = tile_max(st);
;     lsum = exp_pack(st, m, P);
;   }
.LBB0_468:
	s_lshl_b32 s1, s12, 5
	s_and_b32 s0, s12, 0xffffff00
	s_and_b32 s1, s1, 0xe0
	s_or_b32 s0, s1, s0
	s_bfe_u32 s1, s12, 0x50003
	v_mov_b32_e32 v38, v158
	s_or_b32 s2, s0, s1
	s_and_b64 s[0:1], s[6:7], exec
	v_lshlrev_b32_e32 v2, 1, v38
	v_lshrrev_b32_e32 v34, 1, v38
	v_and_b32_e32 v0, 19, v38
	v_and_b32_e32 v2, 8, v2
	v_and_b32_e32 v3, 4, v34
	s_load_dwordx2 s[10:11], s[80:81], 0xf8
	s_cselect_b32 s2, s2, s12
	v_or3_b32 v0, v2, v0, v3
	s_ashr_i32 s13, s2, 8
	v_readfirstlane_b32 s1, v38
	v_bfe_u32 v144, v38, 5, 1
	s_lshl_b32 s4, s2, 7
	v_lshrrev_b32_e32 v23, 1, v0
	s_ashr_i32 s15, s1, 6
	v_and_b32_e32 v35, 31, v38
	s_lshl_b32 s16, s13, 13
	s_and_b32 s4, s4, 0x1f80
	v_lshlrev_b32_e32 v22, 7, v0
	v_bitop3_b32 v0, v23, v144, 7 bitop3:0x6c
	s_ashr_i32 s1, s1, 7
	s_and_b32 s14, s2, 0xffffff00
	s_or_b32 s4, s16, s4
	v_lshl_or_b32 v141, v0, 4, v22
	v_lshl_or_b32 v0, s1, 5, v35
	s_lshl_b32 s2, s2, 1
	v_add_u32_e32 v134, s4, v0
	s_load_dwordx2 s[4:5], s[80:81], 0x108
	s_waitcnt lgkmcnt(0)
	v_mov_b64_e32 v[2:3], s[10:11]
	s_and_b32 s17, s2, 0x180
	s_and_b32 s0, s15, 1
	v_mad_i64_i32 v[2:3], s[18:19], v134, s45, v[2:3]
	s_lshl_b32 s42, s17, 1
	v_lshl_add_u64 v[2:3], v[2:3], 0, s[42:43]
	s_lshl_b32 s18, s0, 7
	s_mov_b32 s19, s43
	v_lshl_add_u64 v[2:3], v[2:3], 0, s[18:19]
	v_lshlrev_b32_e32 v132, 4, v144
	v_mov_b32_e32 v133, v1
	v_lshl_add_u64 v[2:3], v[2:3], 0, v[132:133]
	v_mov_b64_e32 v[136:137], v[2:3]
	s_lshl_b32 s18, s13, 9
	s_or_b32 s2, s17, s18
	s_add_i32 s3, s14, 0x4000
	s_mul_hi_i32 s13, s2, 0x4200
	s_mulk_i32 s2, 0x4200
	v_bfe_u32 v36, v38, 3, 3
	s_add_u32 s20, s4, s2
	v_lshl_or_b32 v2, s15, 3, v36
	s_addc_u32 s21, s5, s13
	v_lshrrev_b32_e32 v0, 1, v2
	s_mul_i32 s24, s14, 0x1600
	s_add_u32 s10, s10, s42
	v_xor_b32_e32 v0, v0, v38
	s_addc_u32 s11, s11, 0
	v_lshlrev_b32_e32 v0, 4, v0
	s_add_i32 s13, s24, 0x5800000
	v_and_b32_e32 v37, 0x70, v0
	v_mul_lo_u32 v0, v2, s45
	s_mul_hi_i32 s2, s3, 0x1600
	s_add_u32 s22, s10, s13
	v_or_b32_e32 v0, v37, v0
	s_addc_u32 s23, s11, s2
	s_lshl_b32 s2, s15, 10
	v_lshl_add_u64 v[4:5], s[22:23], 0, v[0:1]
	s_add_i32 s13, s2, 0
	v_lshl_add_u64 v[6:7], v[4:5], 0, s[96:97]
	s_mov_b32 m0, s13
	v_mul_lo_u32 v2, v2, s65
	s_waitcnt vmcnt(0)
	s_barrier
	global_load_dwordx4 v[98:101], v[136:137], off offset:1024
	global_load_dwordx4 v[102:105], v[136:137], off offset:1056
	global_load_dwordx4 v[106:109], v[136:137], off offset:1088
	global_load_dwordx4 v[110:113], v[136:137], off offset:1120
	global_load_lds_dwordx4 v[6:7], off
	v_lshl_add_u64 v[4:5], v[4:5], 0, s[52:53]
	s_add_i32 m0, s13, 0x2000
	v_or_b32_e32 v2, v37, v2
	v_mov_b32_e32 v3, v1
	global_load_lds_dwordx4 v[4:5], off
	s_add_i32 m0, s13, 0x4000
	v_lshl_add_u64 v[8:9], s[20:21], 0, v[2:3]
	global_load_lds_dwordx4 v2, s[20:21]
	s_mov_b64 s[20:21], 0x108000
	s_add_i32 m0, s13, 0x6000
	s_addk_i32 s14, 0x4040
	s_add_i32 s24, s24, 0x5858000
	v_lshl_add_u64 v[2:3], v[8:9], 0, s[20:21]
	s_mul_hi_i32 s2, s14, 0x1600
	s_add_u32 s20, s10, s24
	s_addc_u32 s21, s11, s2
	global_load_lds_dwordx4 v[2:3], off
	v_lshl_add_u64 v[2:3], s[20:21], 0, v[0:1]
	v_lshl_add_u64 v[4:5], v[2:3], 0, s[96:97]
	s_add_i32 m0, s13, 0x8000
	v_lshl_add_u64 v[2:3], v[2:3], 0, s[52:53]
	global_load_lds_dwordx4 v[4:5], off
	s_add_i32 m0, s13, 0xa000
	v_lshl_add_u64 v[6:7], v[8:9], 0, s[46:47]
	global_load_lds_dwordx4 v[2:3], off
	s_add_i32 m0, s13, 0xc000
	s_mov_b64 s[20:21], 0x108080
	s_lshl_b32 s14, s0, 13
	global_load_lds_dwordx4 v[6:7], off
	v_lshl_add_u64 v[2:3], v[8:9], 0, s[20:21]
	s_add_i32 m0, s13, 0xe000
	s_add_i32 s2, s14, 0
	global_load_lds_dwordx4 v[2:3], off
	s_mov_b64 s[20:21], 0x58000
	s_add_i32 m0, s13, 0x10000
	v_lshl_add_u64 v[4:5], v[4:5], 0, s[20:21]
	v_lshl_add_u64 v[6:7], v[4:5], 0, s[46:47]
	global_load_lds_dwordx4 v[4:5], off
	s_add_i32 m0, s13, 0x12000
	s_mov_b64 s[20:21], 0x100
	global_load_lds_dwordx4 v[6:7], off
	v_lshl_add_u64 v[4:5], v[8:9], 0, s[20:21]
	s_add_i32 m0, s13, 0x14000
	s_mov_b64 s[20:21], 0x108100
	global_load_lds_dwordx4 v[4:5], off
	v_lshl_add_u64 v[6:7], v[8:9], 0, s[20:21]
	s_add_i32 m0, s13, 0x16000
	s_nop 0
	global_load_lds_dwordx4 v[6:7], off
	v_add_u32_e32 v24, s2, v141
	s_waitcnt vmcnt(8)
	s_barrier
	ds_read_b128 v[2:5], v24
	v_or_b32_e32 v39, 2, v144
	v_bitop3_b32 v6, v23, v39, 7 bitop3:0x6c
	v_lshl_or_b32 v145, v6, 4, v22
	v_add_u32_e32 v42, s2, v145
	ds_read_b128 v[18:21], v42
	s_waitcnt vmcnt(8) lgkmcnt(0)
	v_mfma_f32_32x32x16_bf16 v[2:17], v[2:5], v[98:101], 0
	v_or_b32_e32 v40, 4, v144
	v_bitop3_b32 v25, v23, v40, 7 bitop3:0x6c
	v_lshl_or_b32 v147, v25, 4, v22
	v_add_u32_e32 v46, s2, v147
	v_or_b32_e32 v41, 6, v144
	v_bitop3_b32 v23, v23, v41, 7 bitop3:0x6c
	v_lshl_or_b32 v148, v23, 4, v22
	v_mfma_f32_32x32x16_bf16 v[2:17], v[18:21], v[102:105], v[2:17]
	ds_read_b128 v[18:21], v46
	v_add_u32_e32 v47, s2, v148
	ds_read_b128 v[42:45], v42 offset:4096
	s_cmp_lt_i32 s15, 4
	s_waitcnt lgkmcnt(1)
	v_mfma_f32_32x32x16_bf16 v[2:17], v[18:21], v[106:109], v[2:17]
	ds_read_b128 v[18:21], v47
	s_waitcnt lgkmcnt(0)
	v_mfma_f32_32x32x16_bf16 v[2:17], v[18:21], v[110:113], v[2:17]
	ds_read_b128 v[18:21], v24 offset:4096
	s_waitcnt lgkmcnt(0)
	v_mfma_f32_32x32x16_bf16 v[18:33], v[18:21], v[98:101], 0
	v_mfma_f32_32x32x16_bf16 v[18:33], v[42:45], v[102:105], v[18:33]
	ds_read_b128 v[42:45], v46 offset:4096
	s_waitcnt lgkmcnt(0)
	v_mfma_f32_32x32x16_bf16 v[18:33], v[42:45], v[106:109], v[18:33]
	ds_read_b128 v[42:45], v47 offset:4096
	s_waitcnt lgkmcnt(0)
	v_mfma_f32_32x32x16_bf16 v[18:33], v[42:45], v[110:113], v[18:33]
	s_nop 1
	v_max_f32_e32 v42, v3, v3
	v_max_f32_e32 v43, v2, v2
	v_max_f32_e32 v42, v43, v42
	v_max3_f32 v42, v42, v4, v5
	v_max3_f32 v42, v42, v6, v7
	v_max3_f32 v42, v42, v8, v9
	v_max3_f32 v42, v42, v10, v11
	v_max3_f32 v42, v42, v12, v13
	v_max3_f32 v42, v42, v14, v15
	v_max3_f32 v42, v42, v16, v17
	v_max3_f32 v42, v42, v18, v19
	v_max3_f32 v42, v42, v20, v21
	v_max3_f32 v42, v42, v22, v23
	v_max3_f32 v42, v42, v24, v25
	v_max3_f32 v42, v42, v26, v27
	v_max3_f32 v42, v42, v28, v29
	v_max3_f32 v42, v42, v30, v31
	v_max3_f32 v42, v42, v32, v33
	v_mul_f32_e32 v42, 1.0, v42
	v_mov_b32_e32 v43, v42
	s_nop 1
	v_permlane32_swap_b32_e32 v42, v43
	s_cbranch_scc1 .LBB0_470
	s_nop 0

; #define MFMA32(a, b, c) __builtin_amdgcn_mfma_f32_32x32x16_bf16((a), (b), (c), 0, 0, 0)
; #define VLOAD(dst, sbv, q) do { _Pragma("unroll") for (int d_ = 0; d_ < 4; ++d_) dst[d_] = *(const lds_bf16x8*)((sbv) + vo[q] + d_ * 4096); } while (0)
; #define FENCE __builtin_amdgcn_sched_barrier(0)
; DI void diff_unit(KP p, int l, int b, int h, int qb, int isctx, float lamv, float lam_init, char* ldsc) {
;     ...
;     f32x16 st[2];
; #pragma unroll
;     for (int t = 0; t < 2; ++t)
; #pragma unroll
;       for (int ks = 0; ks < 4; ++ks) kf[t][ks] = *(const lds_bf16x8*)(sbk + ko[ks] + t * 4096);
;     FENCE;
;     pv_grp(o, vA, P[0]); pv_grp(o, vB, P[1]);
;     VLOAD(vA, sbv, 2); VLOAD(vB, sbv, 3);
;     FENCE;
; #pragma unroll
;     for (int i = 0; i < 16; ++i) { st[0][i] = 0.f; st[1][i] = 0.f; }
; #pragma unroll
;     for (int ks = 0; ks < 4; ++ks) st[0] = MFMA32(kf[0][ks], qf[ks], st[0]);
; #pragma unroll
;     for (int ks = 0; ks < 4; ++ks) st[1] = MFMA32(kf[1][ks], qf[ks], st[1]);
;     FENCE;
;     pv_grp(o, vA, P[2]);
;     const float mx = tile_max(st);
;     need = !__all(mx <= m + 8.0f);
;     const float mn = need ? fmaxf(m, mx) : m;
;     alpha = __builtin_amdgcn_exp2f(m - mn);
;     FENCE;
;     float ps = exp_pack1<0>(st, mn, P[0]);
;     ps += exp_pack1<1>(st, mn, P[1]);
;     ps += exp_pack1<2>(st, mn, P[2]);
;     pv_grp(o, vB, P[3]);
;     ps += exp_pack1<3>(st, mn, P[3]);
; #pragma unroll
;     for (int q = 0; q < 4; ++q) { __builtin_amdgcn_sched_group_barrier(0x402, 18, 0); __builtin_amdgcn_sched_group_barrier(0x008, 1, 0); }
;     lsum = lsum * alpha + ps; m = mn;
.LBB0_477:
	s_mov_b64 s[4:5], 0
	s_add_i32 s2, s17, 1
	s_and_b32 s16, s2, 3
	s_lshl_b32 s2, s16, 15
	s_add_i32 s15, s2, 0
	ds_read_b128 v[154:157], v136
	ds_read_b128 v[192:195], v136 offset:4096
	ds_read_b128 v[196:199], v137
	ds_read_b128 v[200:203], v137 offset:4096
	ds_read_b128 v[204:207], v138
	ds_read_b128 v[208:211], v138 offset:4096
	ds_read_b128 v[212:215], v139
	ds_read_b128 v[216:219], v139 offset:4096
	s_waitcnt lgkmcnt(8)
	v_mfma_f32_32x32x16_bf16 v[50:65], v[86:89], v[66:69], v[50:65]
	ds_read_b128 v[220:223], v248 offset:24576
	ds_read_b128 v[224:227], v248 offset:28672
	s_add_i32 s18, s3, 0xc0
	s_add_i32 s19, s10, 64
	s_cmp_eq_u32 s11, 0
	s_cselect_b32 s19, s18, s19
	s_mul_i32 s19, s19, 0x1600
	s_add_u32 s18, s22, s19
	s_addc_u32 s19, s23, 0
	s_add_i32 s24, s17, 3
	s_and_b32 s24, s24, 3
	s_lshl_b32 s24, s24, 15
	s_add_i32 s24, s13, s24
	s_mov_b32 m0, s24
	v_mfma_f32_32x32x16_bf16 v[34:49], v[82:85], v[66:69], v[34:49]
	global_load_lds_dwordx4 v244, s[18:19]
	s_add_i32 m0, s24, 0x2000
	v_mfma_f32_32x32x16_bf16 v[18:33], v[78:81], v[66:69], v[18:33]
	v_mfma_f32_32x32x16_bf16 v[2:17], v[74:77], v[66:69], v[2:17]
	v_mov_b64_e32 v[66:67], v[252:253]
	v_mov_b64_e32 v[68:69], v[252:253]
	v_mov_b64_e32 v[74:75], v[252:253]
	global_load_lds_dwordx4 v245, s[18:19]
	s_add_i32 m0, s24, 0x4000
	v_mfma_f32_32x32x16_bf16 v[50:65], v[126:129], v[70:73], v[50:65]
	v_mov_b64_e32 v[76:77], v[252:253]
	v_mov_b64_e32 v[78:79], v[252:253]
	v_mov_b64_e32 v[80:81], v[252:253]
	ds_read_b128 v[126:129], v248 offset:20480
	v_mfma_f32_32x32x16_bf16 v[34:49], v[122:125], v[70:73], v[34:49]
	v_mov_b64_e32 v[82:83], v[252:253]
	v_mov_b64_e32 v[84:85], v[252:253]
	ds_read_b128 v[122:125], v248 offset:16384
	ds_read_b128 v[228:231], v255 offset:16384
	ds_read_b128 v[232:235], v255 offset:20480
	ds_read_b128 v[236:239], v255 offset:24576
	ds_read_b128 v[240:243], v255 offset:28672
	v_mfma_f32_32x32x16_bf16 v[18:33], v[94:97], v[70:73], v[18:33]
	v_mov_b64_e32 v[86:87], v[252:253]
	v_mov_b64_e32 v[88:89], v[252:253]
	v_mov_b64_e32 v[94:95], v[252:253]
	v_mov_b64_e32 v[96:97], v[252:253]
	v_mfma_f32_32x32x16_bf16 v[2:17], v[90:93], v[70:73], v[2:17]
	v_mov_b64_e32 v[70:71], v[252:253]
	v_mov_b64_e32 v[72:73], v[252:253]
	v_mov_b64_e32 v[90:91], v[252:253]
	v_mov_b64_e32 v[92:93], v[252:253]
	global_load_lds_dwordx4 v246, s[20:21]
	s_add_i32 m0, s24, 0x6000
	s_waitcnt lgkmcnt(8)
	v_mfma_f32_32x32x16_bf16 v[66:81], v[192:195], v[98:101], v[66:81]
	v_mfma_f32_32x32x16_bf16 v[82:97], v[154:157], v[98:101], v[82:97]
	v_mfma_f32_32x32x16_bf16 v[66:81], v[200:203], v[102:105], v[66:81]
	v_mfma_f32_32x32x16_bf16 v[82:97], v[196:199], v[102:105], v[82:97]
	global_load_lds_dwordx4 v247, s[20:21]
	s_add_u32 s20, s20, 0x80
	s_addc_u32 s21, s21, 0
	v_mfma_f32_32x32x16_bf16 v[66:81], v[208:211], v[106:109], v[66:81]
	v_mfma_f32_32x32x16_bf16 v[82:97], v[204:207], v[106:109], v[82:97]
	v_mfma_f32_32x32x16_bf16 v[66:81], v[216:219], v[110:113], v[66:81]
	v_mfma_f32_32x32x16_bf16 v[82:97], v[212:215], v[110:113], v[82:97]
	s_waitcnt lgkmcnt(0)
	v_mfma_f32_32x32x16_bf16 v[50:65], v[122:125], v[118:121], v[50:65]
	v_add_u32_e32 v251, s15, v150
	v_add_u32_e32 v249, s15, v151
	s_add_i32 s18, s16, 1
	s_and_b32 s18, s18, 3
	s_lshl_b32 s18, s18, 15
	s_add_i32 s18, s18, s14
	v_add_u32_e32 v136, s18, v141
	v_add_u32_e32 v137, s18, v145
	v_add_u32_e32 v138, s18, v147
	v_add_u32_e32 v139, s18, v148
	s_lshl_b32 s19, s16, 15
	v_add_u32_e32 v248, s19, v149
	v_add_u32_e32 v255, s19, v146
	v_mfma_f32_32x32x16_bf16 v[34:49], v[126:129], v[118:121], v[34:49]
	v_exp_f32_e32 v122, v82
	v_exp_f32_e32 v124, v83
	v_exp_f32_e32 v126, v84
	v_exp_f32_e32 v128, v85
	v_exp_f32_e32 v156, v86
	v_mfma_f32_32x32x16_bf16 v[18:33], v[220:223], v[118:121], v[18:33]
	v_exp_f32_e32 v192, v87
	v_exp_f32_e32 v194, v88
	v_exp_f32_e32 v196, v89
	v_exp_f32_e32 v123, v90
	v_exp_f32_e32 v125, v91
	v_mfma_f32_32x32x16_bf16 v[2:17], v[224:227], v[118:121], v[2:17]
	v_exp_f32_e32 v127, v92
	v_exp_f32_e32 v129, v93
	v_exp_f32_e32 v157, v94
	v_exp_f32_e32 v193, v95
	v_exp_f32_e32 v195, v96
	v_mfma_f32_32x32x16_bf16 v[50:65], v[228:231], v[114:117], v[50:65]
	v_exp_f32_e32 v197, v97
	v_exp_f32_e32 v83, v66
	v_exp_f32_e32 v67, v67
	v_exp_f32_e32 v85, v68
	v_exp_f32_e32 v69, v69
	v_mfma_f32_32x32x16_bf16 v[34:49], v[232:235], v[114:117], v[34:49]
	v_exp_f32_e32 v87, v70
	v_exp_f32_e32 v71, v71
	v_exp_f32_e32 v89, v72
	v_exp_f32_e32 v73, v73
	v_pk_add_f32 v[92:93], v[124:125], v[122:123]
	v_pk_add_f32 v[92:93], v[126:127], v[92:93]
	v_mfma_f32_32x32x16_bf16 v[18:33], v[236:239], v[114:117], v[18:33]
	v_exp_f32_e32 v82, v74
	v_exp_f32_e32 v66, v75
	v_exp_f32_e32 v84, v76
	v_exp_f32_e32 v68, v77
	v_pk_add_f32 v[92:93], v[128:129], v[92:93]
	v_pk_add_f32 v[92:93], v[156:157], v[92:93]
	v_mfma_f32_32x32x16_bf16 v[2:17], v[240:243], v[114:117], v[2:17]
	v_exp_f32_e32 v86, v78
	v_exp_f32_e32 v70, v79
	v_exp_f32_e32 v88, v80
	v_exp_f32_e32 v72, v81
	v_pk_add_f32 v[92:93], v[192:193], v[92:93]
	v_pk_add_f32 v[92:93], v[194:195], v[92:93]
	v_pk_add_f32 v[92:93], v[196:197], v[92:93]
	ds_read_b128 v[78:81], v251 offset:24576
	ds_read_b128 v[74:77], v251 offset:28672
	v_pk_add_f32 v[198:199], v[66:67], v[82:83]
	v_pk_add_f32 v[198:199], v[84:85], v[198:199]
	v_pk_add_f32 v[198:199], v[68:69], v[198:199]
	v_pk_add_f32 v[198:199], v[86:87], v[198:199]
	v_pk_add_f32 v[198:199], v[70:71], v[198:199]
	v_pk_add_f32 v[198:199], v[88:89], v[198:199]
	v_pk_add_f32 v[198:199], v[72:73], v[198:199]
	v_pk_add_f32 v[198:199], v[198:199], v[92:93]
	v_max_f32_e32 v200, v198, v199
	v_cmp_lt_f32_e32 vcc, 0x43000000, v200
	s_cmp_lg_u64 vcc, 0
	s_cbranch_scc1 .Ldiff_rare
; #define VLOAD(dst, sbv, q) do { _Pragma("unroll") for (int d_ = 0; d_ < 4; ++d_) dst[d_] = *(const lds_bf16x8*)((sbv) + vo[q] + d_ * 4096); } while (0)
; #define FENCE __builtin_amdgcn_sched_barrier(0)
; DI void diff_unit(KP p, int l, int b, int h, int qb, int isctx, float lamv, float lam_init, char* ldsc) {
;     ...
;     pv_grp(o, vA, P[2]);
;     const float mx = tile_max(st);
;     need = !__all(mx <= m + 8.0f);
;     const float mn = need ? fmaxf(m, mx) : m;
;     alpha = __builtin_amdgcn_exp2f(m - mn);
;     FENCE;
;     float ps = exp_pack1<0>(st, mn, P[0]);
;     ps += exp_pack1<1>(st, mn, P[1]);
;     ps += exp_pack1<2>(st, mn, P[2]);
;     pv_grp(o, vB, P[3]);
;     ps += exp_pack1<3>(st, mn, P[3]);
; #pragma unroll
;     for (int q = 0; q < 4; ++q) { __builtin_amdgcn_sched_group_barrier(0x402, 18, 0); __builtin_amdgcn_sched_group_barrier(0x008, 1, 0); }
;     lsum = lsum * alpha + ps; m = mn;
;     FENCE;
;     { const lds_u8* sbn = L + stg1 * STG + 16384; VLOAD(vA, sbn, 0); VLOAD(vB, sbn, 1); }
.Ldiff_rare_back:
	v_cvt_pk_bf16_f32 v118, v83, v67
	v_cvt_pk_bf16_f32 v114, v82, v66
	v_cvt_pk_bf16_f32 v119, v85, v69
	v_cvt_pk_bf16_f32 v120, v87, v71
	v_cvt_pk_bf16_f32 v121, v89, v73
	v_cvt_pk_bf16_f32 v115, v84, v68
	v_cvt_pk_bf16_f32 v116, v86, v70
	v_cvt_pk_bf16_f32 v117, v88, v72
	ds_read_b128 v[86:89], v251 offset:16384
	ds_read_b128 v[82:85], v251 offset:20480
	v_cvt_pk_bf16_f32 v66, v122, v124
	v_cvt_pk_bf16_f32 v67, v126, v128
	v_cvt_pk_bf16_f32 v70, v123, v125
	v_cvt_pk_bf16_f32 v71, v127, v129
	ds_read_b128 v[126:129], v249 offset:16384
	ds_read_b128 v[122:125], v249 offset:20480
	v_pk_add_f32 v[152:153], v[152:153], v[198:199]
	ds_read_b128 v[94:97], v249 offset:24576
	ds_read_b128 v[90:93], v249 offset:28672
	s_add_i32 s11, s11, 1
	s_add_i32 s10, s10, 64
	v_cvt_pk_bf16_f32 v68, v156, v192
	v_cvt_pk_bf16_f32 v69, v194, v196
	v_cvt_pk_bf16_f32 v72, v157, v193
	v_cvt_pk_bf16_f32 v73, v195, v197
	s_cmpk_eq_i32 s11, 0x83
	s_cbranch_scc1 .LBB0_479
	s_mov_b32 s17, s16
	s_branch .LBB0_471
.Ldiff_rare:
	v_max3_f32 v201, v66, v67, v82
	v_max3_f32 v201, v201, v83, v84
	v_max3_f32 v201, v201, v85, v68
	v_max3_f32 v201, v201, v69, v86
	v_max3_f32 v201, v201, v87, v70
	v_max3_f32 v201, v201, v71, v88
	v_max3_f32 v201, v201, v89, v72
	v_max3_f32 v201, v201, v73, v122
	v_max3_f32 v201, v201, v123, v124
	v_max3_f32 v201, v201, v125, v126
	v_max3_f32 v201, v201, v127, v128
	v_max3_f32 v201, v201, v129, v156
	v_max3_f32 v201, v201, v157, v192
	v_max3_f32 v201, v201, v193, v194
	v_max3_f32 v201, v201, v195, v196
	v_max_f32_e32 v201, v201, v197
	v_mov_b32_e32 v202, v201
	s_nop 1
	v_permlane32_swap_b32_e32 v201, v202
	v_max_f32_e32 v201, v201, v202
	v_frexp_exp_i32_f32_e32 v202, v201
	v_max_i32_e32 v202, 0, v202
	v_sub_u32_e32 v203, 0, v202
	v_ldexp_f32 v140, 1.0, v203
	v_cvt_f32_i32_e32 v203, v202
	v_sub_f32_e32 v252, v252, v203
	v_mov_b32_e32 v253, v252
	v_pk_mul_f32 v[66:67], v[66:67], v[140:141] op_sel_hi:[1,0]
	v_pk_mul_f32 v[82:83], v[82:83], v[140:141] op_sel_hi:[1,0]
	v_pk_mul_f32 v[84:85], v[84:85], v[140:141] op_sel_hi:[1,0]
	v_pk_mul_f32 v[68:69], v[68:69], v[140:141] op_sel_hi:[1,0]
	v_pk_mul_f32 v[86:87], v[86:87], v[140:141] op_sel_hi:[1,0]
	v_pk_mul_f32 v[70:71], v[70:71], v[140:141] op_sel_hi:[1,0]
	v_pk_mul_f32 v[88:89], v[88:89], v[140:141] op_sel_hi:[1,0]
	v_pk_mul_f32 v[72:73], v[72:73], v[140:141] op_sel_hi:[1,0]
	v_pk_mul_f32 v[122:123], v[122:123], v[140:141] op_sel_hi:[1,0]
	v_pk_mul_f32 v[124:125], v[124:125], v[140:141] op_sel_hi:[1,0]
	v_pk_mul_f32 v[126:127], v[126:127], v[140:141] op_sel_hi:[1,0]
	v_pk_mul_f32 v[128:129], v[128:129], v[140:141] op_sel_hi:[1,0]
	v_pk_mul_f32 v[156:157], v[156:157], v[140:141] op_sel_hi:[1,0]
	v_pk_mul_f32 v[192:193], v[192:193], v[140:141] op_sel_hi:[1,0]
	v_pk_mul_f32 v[194:195], v[194:195], v[140:141] op_sel_hi:[1,0]
	v_pk_mul_f32 v[196:197], v[196:197], v[140:141] op_sel_hi:[1,0]
	v_pk_mul_f32 v[198:199], v[198:199], v[140:141] op_sel_hi:[1,0]
	v_pk_mul_f32 v[152:153], v[152:153], v[140:141] op_sel_hi:[1,0]
	s_mov_b64 s[4:5], -1
	s_branch .Ldiff_rare_back
